# attention: next tile's LDS stores hoisted into the QK MFMA section (off the tile-boundary critical path)
# baseline (speedup 1.0000x reference)
; #define LAS __attribute__((address_space(3)))
; __device__ __forceinline__ void attn_phase(const Args& a, LAS unsigned char* lds, const bf16* Qn, const bf16* Kn, const bf16* Vt, bf16* O, float* stash, int tid, int lane, int wave) {
;     ...
;                 if (t + 2 < NT) { kreg[hh] = gload16_asm(Kp + (size_t)(t + 2) * 4096); vreg0[hh] = gload16_asm(Vp + 64 * (t + 2)); vreg1[hh] = gload16_asm(Vp + (size_t)64 * SEQ + 64 * (t + 2)); }
;                 if (t <= td) {
;                     const LAS unsigned char* kb = lds + (t & 1) * AT_BUF + n32 * 144 + hi * 16;
;                     f32x16 p0, p1;
; #pragma unroll
;                     for (int r = 0; r < 16; ++r) { p0[r] = 0.f; p1[r] = 0.f; }
;                     bf16x8 kf0[4], kf1[4];
; #pragma unroll
;                     for (int ds = 0; ds < 4; ++ds) { kf0[ds] = *(const LAS bf16x8*)(kb + ds * 32); kf1[ds] = *(const LAS bf16x8*)(kb + 32 * 144 + ds * 32); }
;                     const LAS unsigned char* vb = lds + (t & 1) * AT_BUF + AT_KB + n32 * 144 + hi * 16;
;                     bf16x8 vf[2][4];
; #pragma unroll
;                     for (int i = 0; i < 4; ++i) vf[0][i] = *(const LAS bf16x8*)(vb + i * 32 * 144);
;                     __builtin_amdgcn_sched_barrier(0);
;                     #pragma unroll
;                     for (int ds = 0; ds < 4; ++ds) {
;                         p0 = __builtin_amdgcn_mfma_f32_32x32x16_bf16(kf0[ds], qf[ds], p0, 0, 0, 0);
;                         p1 = __builtin_amdgcn_mfma_f32_32x32x16_bf16(kf1[ds], qf[ds], p1, 0, 0, 0);
;                     }
;                                         __builtin_amdgcn_sched_barrier(0);
;                     if (t == td) {
;                         asm volatile("" ::: "memory");
; #pragma unroll
;                         for (int r = 0; r < 16; ++r) { const int key = (r & 3) + 8 * (r >> 2) + 4 * hi; if (key > qloc) p0[r] = -INFINITY; if (key + 32 > qloc) p1[r] = -INFINITY; }
;                     }
;     ...
;                 if (t + 1 < NT) { if (t + 2 < NT) asm volatile("s_waitcnt vmcnt(3)" ::: "memory"); else asm volatile("s_waitcnt vmcnt(0)" ::: "memory");
;                     LAS unsigned char* d = lds + ((t + 1) & 1) * AT_BUF; *(LAS u32x4*)(d + kofs) = kreg[hh ^ 1]; *(LAS u32x4*)(d + AT_KB + kofs) = vreg0[hh ^ 1]; *(LAS u32x4*)(d + AT_KB + 64 * 144 + kofs) = vreg1[hh ^ 1]; }
.LBB0_110:
	v_add_u32_e32 v0, v161, v160
	ds_read_b128 v[80:83], v0
	ds_read_b128 v[198:201], v0 offset:32
	ds_read_b128 v[84:87], v0 offset:4608
	ds_read_b128 v[202:205], v0 offset:4640
	ds_read_b128 v[206:209], v0 offset:64
	ds_read_b128 v[210:213], v0 offset:96
	ds_read_b128 v[218:221], v0 offset:4672
	ds_read_b128 v[222:225], v0 offset:4704
	ds_read_b128 v[152:155], v0 offset:9216
	ds_read_b128 v[10:13], v0 offset:13824
	ds_read_b128 v[6:9], v0 offset:18432
	ds_read_b128 v[2:5], v0 offset:23040
	s_waitcnt lgkmcnt(11)
	v_mfma_f32_32x32x16_bf16 v[96:111], v[80:83], v[112:115], v[226:241]
	s_waitcnt lgkmcnt(9)
	v_mfma_f32_32x32x16_bf16 v[80:95], v[84:87], v[112:115], v[226:241]
	v_mfma_f32_32x32x16_bf16 v[96:111], v[198:201], v[116:119], v[96:111]
	s_add_i32 s22, s2, 1
	s_cmp_ge_u32 s22, s33
	s_cbranch_scc1 .Lat_nw_a
	s_and_b64 vcc, exec, s[20:21]
	s_cbranch_vccz .Lat_w3_a
	s_waitcnt vmcnt(0)
	s_branch .Lat_w_a
.Lat_w3_a:
	s_waitcnt vmcnt(3)
.Lat_w_a:
	ds_write_b128 v195, v[128:131] offset:27648
	ds_write_b128 v195, v[136:139] offset:36864
	ds_write_b128 v195, v[144:147] offset:46080
.Lat_nw_a:
	s_waitcnt lgkmcnt(8)
	v_mfma_f32_32x32x16_bf16 v[80:95], v[202:205], v[116:119], v[80:95]
	s_waitcnt lgkmcnt(7)
	v_mfma_f32_32x32x16_bf16 v[96:111], v[206:209], v[120:123], v[96:111]
	s_waitcnt lgkmcnt(5)
	v_mfma_f32_32x32x16_bf16 v[80:95], v[218:221], v[120:123], v[80:95]
	v_mfma_f32_32x32x16_bf16 v[96:111], v[210:213], v[124:127], v[96:111]
	s_waitcnt lgkmcnt(4)
	v_mfma_f32_32x32x16_bf16 v[80:95], v[222:225], v[124:127], v[80:95]
	ds_read_b128 v[198:201], v0 offset:9248
	ds_read_b128 v[202:205], v0 offset:13856
	ds_read_b128 v[206:209], v0 offset:18464
	ds_read_b128 v[210:213], v0 offset:23072
	s_nop 7
	s_cmp_lg_u32 s30, s2
	s_cbranch_scc1 .Lat_nodiag_a
	v_cndmask_b32_e64 v14, v96, v248, s[42:43]
	v_cndmask_b32_e64 v80, v80, v248, s[44:45]
	v_cndmask_b32_e64 v97, v248, v97, s[46:47]
	v_cndmask_b32_e64 v96, v14, v96, s[46:47]
	v_cndmask_b32_e64 v81, v81, v248, s[48:49]
	v_cndmask_b32_e64 v98, v98, v248, s[50:51]
	v_cndmask_b32_e64 v82, v82, v248, s[52:53]
	v_cndmask_b32_e64 v99, v99, v248, s[54:55]
	v_cndmask_b32_e64 v83, v83, v248, s[56:57]
	v_cndmask_b32_e64 v100, v100, v248, s[58:59]
	v_cndmask_b32_e64 v84, v84, v248, s[60:61]
	v_cndmask_b32_e64 v101, v101, v248, s[62:63]
	v_cndmask_b32_e64 v85, v85, v248, s[64:65]
	v_cndmask_b32_e64 v102, v102, v248, s[66:67]
	v_cndmask_b32_e64 v86, v86, v248, s[68:69]
	v_cndmask_b32_e64 v103, v103, v248, s[70:71]
	v_cndmask_b32_e64 v87, v87, v248, s[72:73]
	v_cndmask_b32_e64 v104, v104, v248, s[74:75]
	v_cndmask_b32_e64 v88, v88, v248, s[76:77]
	v_cndmask_b32_e64 v105, v105, v248, s[78:79]
	v_cndmask_b32_e64 v89, v89, v248, s[80:81]
	v_cndmask_b32_e64 v106, v106, v248, s[82:83]
	v_cndmask_b32_e64 v90, v90, v248, s[84:85]
	v_cndmask_b32_e64 v107, v107, v248, s[86:87]
	v_cndmask_b32_e64 v91, v91, v248, s[88:89]
	v_cndmask_b32_e64 v108, v108, v248, s[90:91]
	v_cndmask_b32_e64 v92, v92, v248, s[92:93]
	v_cndmask_b32_e64 v109, v109, v248, s[94:95]
	v_cndmask_b32_e64 v93, v93, v248, s[96:97]
	v_cndmask_b32_e64 v110, v110, v248, s[6:7]
	v_cndmask_b32_e64 v94, v94, v248, s[8:9]
	v_cndmask_b32_e64 v111, v111, v248, s[10:11]
	v_cndmask_b32_e64 v95, v95, v248, s[12:13]

; #define LAS __attribute__((address_space(3)))
; __device__ __forceinline__ unsigned pk2(float lo, float hi) { f32x2 v = {lo, hi}; bf16x2_t b = __builtin_convertvector(v, bf16x2_t); return __builtin_bit_cast(unsigned, b); }
; __device__ __forceinline__ void attn_phase(const Args& a, LAS unsigned char* lds, const bf16* Qn, const bf16* Kn, const bf16* Vt, bf16* O, float* stash, int tid, int lane, int wave) {
;     ...
; #pragma unroll
;                     for (int r = 0; r < 16; ++r) { p0[r] = __builtin_amdgcn_exp2f(p0[r]); p1[r] = __builtin_amdgcn_exp2f(p1[r]); }
;                     {
;                         const f32x16 ps = p0 + p1;
;                         f32x2 s2 = (f32x2){ps[0], ps[1]} + (f32x2){ps[2], ps[3]};
; #pragma unroll
;                         for (int r = 4; r < 16; r += 2) s2 += (f32x2){ps[r], ps[r + 1]};
;                         lsum += s2.x + s2.y;
;                     }
;                     bf16x8 pf[4];
; #pragma unroll
;                     for (int s4 = 0; s4 < 4; ++s4) {
;                         u32x4 w;
;                         if (s4 < 2) { w.x = pk2(p0[8 * s4 + 0], p0[8 * s4 + 1]); w.y = pk2(p0[8 * s4 + 2], p0[8 * s4 + 3]); w.z = pk2(p0[8 * s4 + 4], p0[8 * s4 + 5]); w.w = pk2(p0[8 * s4 + 6], p0[8 * s4 + 7]); }
;                         else { const int q = s4 - 2; w.x = pk2(p1[8 * q + 0], p1[8 * q + 1]); w.y = pk2(p1[8 * q + 2], p1[8 * q + 3]); w.z = pk2(p1[8 * q + 4], p1[8 * q + 5]); w.w = pk2(p1[8 * q + 6], p1[8 * q + 7]); }
;                         pf[s4] = __builtin_bit_cast(bf16x8, w);
;                     }
; #pragma unroll
;                     for (int s4 = 0; s4 < 4; ++s4) {
;                         if (s4 + 1 < 4) {
; #pragma unroll
;                             for (int i = 0; i < 4; ++i) vf[(s4 + 1) & 1][i] = *(const LAS bf16x8*)(vb + i * 32 * 144 + (s4 + 1) * 32);
;                         }
;                         __builtin_amdgcn_sched_barrier(0);
;                         #pragma unroll
;                         for (int i = 0; i < 4; ++i) o[i] = __builtin_amdgcn_mfma_f32_32x32x16_bf16(vf[s4 & 1][i], pf[s4], o[i], 0, 0, 0);
;                                                 __builtin_amdgcn_sched_barrier(0);
.Lat_noresc_a:
	v_exp_f32_e32 v96, v96
	v_exp_f32_e32 v97, v97
	v_exp_f32_e32 v98, v98
	v_exp_f32_e32 v99, v99
	v_exp_f32_e32 v100, v100
	v_exp_f32_e32 v101, v101
	v_exp_f32_e32 v102, v102
	v_exp_f32_e32 v103, v103
	v_add_f32_e32 v214, v96, v97
	v_add_f32_e32 v215, v98, v99
	v_add_f32_e32 v214, v214, v100
	v_add_f32_e32 v215, v215, v101
	v_add_f32_e32 v214, v214, v102
	v_add_f32_e32 v215, v215, v103
	v_cvt_pk_bf16_f32 v218, v96, v97
	v_cvt_pk_bf16_f32 v219, v98, v99
	v_cvt_pk_bf16_f32 v220, v100, v101
	v_cvt_pk_bf16_f32 v221, v102, v103
	v_add_f32_e32 v197, v197, v214
	v_add_f32_e32 v197, v197, v215
	s_waitcnt lgkmcnt(7)
	v_mfma_f32_32x32x16_bf16 v[64:79], v[152:155], v[218:221], v[64:79]
	v_exp_f32_e32 v104, v104
	v_exp_f32_e32 v105, v105
	v_exp_f32_e32 v106, v106
	v_exp_f32_e32 v107, v107
	v_exp_f32_e32 v108, v108
	s_waitcnt lgkmcnt(6)
	v_mfma_f32_32x32x16_bf16 v[48:63], v[10:13], v[218:221], v[48:63]
	v_exp_f32_e32 v109, v109
	v_exp_f32_e32 v110, v110
	v_exp_f32_e32 v111, v111
	v_add_f32_e32 v214, v104, v105
	v_add_f32_e32 v215, v106, v107
	s_waitcnt lgkmcnt(5)
	v_mfma_f32_32x32x16_bf16 v[32:47], v[6:9], v[218:221], v[32:47]
	v_add_f32_e32 v214, v214, v108
	v_add_f32_e32 v215, v215, v109
	v_add_f32_e32 v214, v214, v110
	v_add_f32_e32 v215, v215, v111
	v_cvt_pk_bf16_f32 v222, v104, v105
	s_waitcnt lgkmcnt(4)
	v_mfma_f32_32x32x16_bf16 v[16:31], v[2:5], v[218:221], v[16:31]
	v_cvt_pk_bf16_f32 v223, v106, v107
	v_cvt_pk_bf16_f32 v224, v108, v109
	v_cvt_pk_bf16_f32 v225, v110, v111
	v_add_f32_e32 v197, v197, v214
	v_add_f32_e32 v197, v197, v215
	ds_read_b128 v[152:155], v0 offset:9280
	ds_read_b128 v[10:13], v0 offset:13888
	ds_read_b128 v[6:9], v0 offset:18496
	ds_read_b128 v[2:5], v0 offset:23104
	s_waitcnt lgkmcnt(7)
	v_mfma_f32_32x32x16_bf16 v[64:79], v[198:201], v[222:225], v[64:79]
	v_exp_f32_e32 v80, v80
	v_exp_f32_e32 v81, v81
	v_exp_f32_e32 v82, v82
	v_exp_f32_e32 v83, v83
	v_exp_f32_e32 v84, v84
	s_waitcnt lgkmcnt(6)
	v_mfma_f32_32x32x16_bf16 v[48:63], v[202:205], v[222:225], v[48:63]
	v_exp_f32_e32 v85, v85
	v_exp_f32_e32 v86, v86
	v_exp_f32_e32 v87, v87
	v_add_f32_e32 v214, v80, v81
	v_add_f32_e32 v215, v82, v83
	s_waitcnt lgkmcnt(5)
	v_mfma_f32_32x32x16_bf16 v[32:47], v[206:209], v[222:225], v[32:47]
	v_add_f32_e32 v214, v214, v84
	v_add_f32_e32 v215, v215, v85
	v_add_f32_e32 v214, v214, v86
	v_add_f32_e32 v215, v215, v87
	v_cvt_pk_bf16_f32 v218, v80, v81
	s_waitcnt lgkmcnt(4)
	v_mfma_f32_32x32x16_bf16 v[16:31], v[210:213], v[222:225], v[16:31]
	v_cvt_pk_bf16_f32 v219, v82, v83
	v_cvt_pk_bf16_f32 v220, v84, v85
	v_cvt_pk_bf16_f32 v221, v86, v87
	v_add_f32_e32 v197, v197, v214
	v_add_f32_e32 v197, v197, v215
	ds_read_b128 v[198:201], v0 offset:9312
	ds_read_b128 v[202:205], v0 offset:13920
	ds_read_b128 v[206:209], v0 offset:18528
	ds_read_b128 v[210:213], v0 offset:23136
	s_waitcnt lgkmcnt(7)
	v_mfma_f32_32x32x16_bf16 v[64:79], v[152:155], v[218:221], v[64:79]
	v_exp_f32_e32 v88, v88
	v_exp_f32_e32 v89, v89
	v_exp_f32_e32 v90, v90
	v_exp_f32_e32 v91, v91
	v_exp_f32_e32 v92, v92
	s_waitcnt lgkmcnt(6)
	v_mfma_f32_32x32x16_bf16 v[48:63], v[10:13], v[218:221], v[48:63]
	v_exp_f32_e32 v93, v93
	v_exp_f32_e32 v94, v94
	v_exp_f32_e32 v95, v95
	v_add_f32_e32 v214, v88, v89
	v_add_f32_e32 v215, v90, v91
	s_waitcnt lgkmcnt(5)
	v_mfma_f32_32x32x16_bf16 v[32:47], v[6:9], v[218:221], v[32:47]
	v_add_f32_e32 v214, v214, v92
	v_add_f32_e32 v215, v215, v93
	v_add_f32_e32 v214, v214, v94
	v_add_f32_e32 v215, v215, v95
	v_cvt_pk_bf16_f32 v222, v88, v89
	s_waitcnt lgkmcnt(4)
	v_mfma_f32_32x32x16_bf16 v[16:31], v[2:5], v[218:221], v[16:31]
	v_cvt_pk_bf16_f32 v223, v90, v91
	v_cvt_pk_bf16_f32 v224, v92, v93
	v_cvt_pk_bf16_f32 v225, v94, v95
	v_add_f32_e32 v197, v197, v214
	v_add_f32_e32 v197, v197, v215
	s_waitcnt lgkmcnt(3)
	v_mfma_f32_32x32x16_bf16 v[64:79], v[198:201], v[222:225], v[64:79]
	s_waitcnt lgkmcnt(2)
	v_mfma_f32_32x32x16_bf16 v[48:63], v[202:205], v[222:225], v[48:63]
	s_waitcnt lgkmcnt(1)
	v_mfma_f32_32x32x16_bf16 v[32:47], v[206:209], v[222:225], v[32:47]
	s_waitcnt lgkmcnt(0)
	v_mfma_f32_32x32x16_bf16 v[16:31], v[210:213], v[222:225], v[16:31]
	s_branch .LBB0_120

; __device__ __forceinline__ void attn_phase(const Args& a, LAS unsigned char* lds, const bf16* Qn, const bf16* Kn, const bf16* Vt, bf16* O, float* stash, int tid, int lane, int wave) {
;     ...
;                 if (t + 2 < NT) { kreg[hh] = gload16_asm(Kp + (size_t)(t + 2) * 4096); vreg0[hh] = gload16_asm(Vp + 64 * (t + 2)); vreg1[hh] = gload16_asm(Vp + (size_t)64 * SEQ + 64 * (t + 2)); }
;                 if (t <= td) {
;                     const LAS unsigned char* kb = lds + (t & 1) * AT_BUF + n32 * 144 + hi * 16;
;                     f32x16 p0, p1;
; #pragma unroll
;                     for (int r = 0; r < 16; ++r) { p0[r] = 0.f; p1[r] = 0.f; }
;                     bf16x8 kf0[4], kf1[4];
; #pragma unroll
;                     for (int ds = 0; ds < 4; ++ds) { kf0[ds] = *(const LAS bf16x8*)(kb + ds * 32); kf1[ds] = *(const LAS bf16x8*)(kb + 32 * 144 + ds * 32); }
;                     const LAS unsigned char* vb = lds + (t & 1) * AT_BUF + AT_KB + n32 * 144 + hi * 16;
;                     bf16x8 vf[2][4];
; #pragma unroll
;                     for (int i = 0; i < 4; ++i) vf[0][i] = *(const LAS bf16x8*)(vb + i * 32 * 144);
;                     __builtin_amdgcn_sched_barrier(0);
;                     #pragma unroll
;                     for (int ds = 0; ds < 4; ++ds) {
;                         p0 = __builtin_amdgcn_mfma_f32_32x32x16_bf16(kf0[ds], qf[ds], p0, 0, 0, 0);
;                         p1 = __builtin_amdgcn_mfma_f32_32x32x16_bf16(kf1[ds], qf[ds], p1, 0, 0, 0);
;                     }
;                                         __builtin_amdgcn_sched_barrier(0);
;                     if (t == td) {
;                         asm volatile("" ::: "memory");
; #pragma unroll
;                         for (int r = 0; r < 16; ++r) { const int key = (r & 3) + 8 * (r >> 2) + 4 * hi; if (key > qloc) p0[r] = -INFINITY; if (key + 32 > qloc) p1[r] = -INFINITY; }
;                     }
;                     asm volatile("s_nop 15\n\ts_nop 7" : "+v"(p0), "+v"(p1));
;     ...
;                 if (t + 1 < NT) { if (t + 2 < NT) asm volatile("s_waitcnt vmcnt(3)" ::: "memory"); else asm volatile("s_waitcnt vmcnt(0)" ::: "memory");
;                     LAS unsigned char* d = lds + ((t + 1) & 1) * AT_BUF; *(LAS u32x4*)(d + kofs) = kreg[hh ^ 1]; *(LAS u32x4*)(d + AT_KB + kofs) = vreg0[hh ^ 1]; *(LAS u32x4*)(d + AT_KB + 64 * 144 + kofs) = vreg1[hh ^ 1]; }
.LBB0_127:
	v_add_u32_e32 v0, v161, v160
	ds_read_b128 v[80:83], v0 offset:27648
	ds_read_b128 v[198:201], v0 offset:27680
	ds_read_b128 v[84:87], v0 offset:32256
	ds_read_b128 v[202:205], v0 offset:32288
	ds_read_b128 v[206:209], v0 offset:27712
	ds_read_b128 v[210:213], v0 offset:27744
	ds_read_b128 v[218:221], v0 offset:32320
	ds_read_b128 v[222:225], v0 offset:32352
	ds_read_b128 v[152:155], v0 offset:36864
	ds_read_b128 v[10:13], v0 offset:41472
	ds_read_b128 v[6:9], v0 offset:46080
	ds_read_b128 v[2:5], v0 offset:50688
	s_waitcnt lgkmcnt(11)
	v_mfma_f32_32x32x16_bf16 v[96:111], v[80:83], v[112:115], v[226:241]
	s_waitcnt lgkmcnt(9)
	v_mfma_f32_32x32x16_bf16 v[80:95], v[84:87], v[112:115], v[226:241]
	v_mfma_f32_32x32x16_bf16 v[96:111], v[198:201], v[116:119], v[96:111]
	s_cmp_gt_u32 s2, s39
	s_cbranch_scc1 .Lat_nw_b
	s_waitcnt vmcnt(3)
	ds_write_b128 v195, v[132:135]
	ds_write_b128 v195, v[140:143] offset:9216
	ds_write_b128 v195, v[148:151] offset:18432
.Lat_nw_b:
	s_waitcnt lgkmcnt(8)
	v_mfma_f32_32x32x16_bf16 v[80:95], v[202:205], v[116:119], v[80:95]
	s_waitcnt lgkmcnt(7)
	v_mfma_f32_32x32x16_bf16 v[96:111], v[206:209], v[120:123], v[96:111]
	s_waitcnt lgkmcnt(5)
	v_mfma_f32_32x32x16_bf16 v[80:95], v[218:221], v[120:123], v[80:95]
	v_mfma_f32_32x32x16_bf16 v[96:111], v[210:213], v[124:127], v[96:111]
	s_waitcnt lgkmcnt(4)
	v_mfma_f32_32x32x16_bf16 v[80:95], v[222:225], v[124:127], v[80:95]
	ds_read_b128 v[198:201], v0 offset:36896
	ds_read_b128 v[202:205], v0 offset:41504
	ds_read_b128 v[206:209], v0 offset:46112
	ds_read_b128 v[210:213], v0 offset:50720
	s_nop 7
	s_cmp_lg_u32 s31, s2
	s_cbranch_scc1 .Lat_nodiag_b
	v_cndmask_b32_e64 v14, v96, v248, s[42:43]
	v_cndmask_b32_e64 v80, v80, v248, s[44:45]
	v_cndmask_b32_e64 v97, v248, v97, s[46:47]
	v_cndmask_b32_e64 v96, v14, v96, s[46:47]
	v_cndmask_b32_e64 v81, v81, v248, s[48:49]
	v_cndmask_b32_e64 v98, v98, v248, s[50:51]
	v_cndmask_b32_e64 v82, v82, v248, s[52:53]
	v_cndmask_b32_e64 v99, v99, v248, s[54:55]
	v_cndmask_b32_e64 v83, v83, v248, s[56:57]
	v_cndmask_b32_e64 v100, v100, v248, s[58:59]
	v_cndmask_b32_e64 v84, v84, v248, s[60:61]
	v_cndmask_b32_e64 v101, v101, v248, s[62:63]
	v_cndmask_b32_e64 v85, v85, v248, s[64:65]
	v_cndmask_b32_e64 v102, v102, v248, s[66:67]
	v_cndmask_b32_e64 v86, v86, v248, s[68:69]
	v_cndmask_b32_e64 v103, v103, v248, s[70:71]
	v_cndmask_b32_e64 v87, v87, v248, s[72:73]
	v_cndmask_b32_e64 v104, v104, v248, s[74:75]
	v_cndmask_b32_e64 v88, v88, v248, s[76:77]
	v_cndmask_b32_e64 v105, v105, v248, s[78:79]
	v_cndmask_b32_e64 v89, v89, v248, s[80:81]
	v_cndmask_b32_e64 v106, v106, v248, s[82:83]
	v_cndmask_b32_e64 v90, v90, v248, s[84:85]
	v_cndmask_b32_e64 v107, v107, v248, s[86:87]
	v_cndmask_b32_e64 v91, v91, v248, s[88:89]
	v_cndmask_b32_e64 v108, v108, v248, s[90:91]
	v_cndmask_b32_e64 v92, v92, v248, s[92:93]
	v_cndmask_b32_e64 v109, v109, v248, s[94:95]
	v_cndmask_b32_e64 v93, v93, v248, s[96:97]
	v_cndmask_b32_e64 v110, v110, v248, s[6:7]
	v_cndmask_b32_e64 v94, v94, v248, s[8:9]
	v_cndmask_b32_e64 v111, v111, v248, s[10:11]
	v_cndmask_b32_e64 v95, v95, v248, s[12:13]

; #define LAS __attribute__((address_space(3)))
; __device__ __forceinline__ unsigned pk2(float lo, float hi) { f32x2 v = {lo, hi}; bf16x2_t b = __builtin_convertvector(v, bf16x2_t); return __builtin_bit_cast(unsigned, b); }
; __device__ __forceinline__ void attn_phase(const Args& a, LAS unsigned char* lds, const bf16* Qn, const bf16* Kn, const bf16* Vt, bf16* O, float* stash, int tid, int lane, int wave) {
;     ...
; #pragma unroll
;                     for (int r = 0; r < 16; ++r) { p0[r] = __builtin_amdgcn_exp2f(p0[r]); p1[r] = __builtin_amdgcn_exp2f(p1[r]); }
;                     {
;                         const f32x16 ps = p0 + p1;
;                         f32x2 s2 = (f32x2){ps[0], ps[1]} + (f32x2){ps[2], ps[3]};
; #pragma unroll
;                         for (int r = 4; r < 16; r += 2) s2 += (f32x2){ps[r], ps[r + 1]};
;                         lsum += s2.x + s2.y;
;                     }
;                     bf16x8 pf[4];
; #pragma unroll
;                     for (int s4 = 0; s4 < 4; ++s4) {
;                         u32x4 w;
;                         if (s4 < 2) { w.x = pk2(p0[8 * s4 + 0], p0[8 * s4 + 1]); w.y = pk2(p0[8 * s4 + 2], p0[8 * s4 + 3]); w.z = pk2(p0[8 * s4 + 4], p0[8 * s4 + 5]); w.w = pk2(p0[8 * s4 + 6], p0[8 * s4 + 7]); }
;                         else { const int q = s4 - 2; w.x = pk2(p1[8 * q + 0], p1[8 * q + 1]); w.y = pk2(p1[8 * q + 2], p1[8 * q + 3]); w.z = pk2(p1[8 * q + 4], p1[8 * q + 5]); w.w = pk2(p1[8 * q + 6], p1[8 * q + 7]); }
;                         pf[s4] = __builtin_bit_cast(bf16x8, w);
;                     }
; #pragma unroll
;                     for (int s4 = 0; s4 < 4; ++s4) {
;                         if (s4 + 1 < 4) {
; #pragma unroll
;                             for (int i = 0; i < 4; ++i) vf[(s4 + 1) & 1][i] = *(const LAS bf16x8*)(vb + i * 32 * 144 + (s4 + 1) * 32);
;                         }
;                         __builtin_amdgcn_sched_barrier(0);
;                         #pragma unroll
;                         for (int i = 0; i < 4; ++i) o[i] = __builtin_amdgcn_mfma_f32_32x32x16_bf16(vf[s4 & 1][i], pf[s4], o[i], 0, 0, 0);
;                                                 __builtin_amdgcn_sched_barrier(0);
.Lat_noresc_b:
	v_exp_f32_e32 v96, v96
	v_exp_f32_e32 v97, v97
	v_exp_f32_e32 v98, v98
	v_exp_f32_e32 v99, v99
	v_exp_f32_e32 v100, v100
	v_exp_f32_e32 v101, v101
	v_exp_f32_e32 v102, v102
	v_exp_f32_e32 v103, v103
	v_add_f32_e32 v214, v96, v97
	v_add_f32_e32 v215, v98, v99
	v_add_f32_e32 v214, v214, v100
	v_add_f32_e32 v215, v215, v101
	v_add_f32_e32 v214, v214, v102
	v_add_f32_e32 v215, v215, v103
	v_cvt_pk_bf16_f32 v218, v96, v97
	v_cvt_pk_bf16_f32 v219, v98, v99
	v_cvt_pk_bf16_f32 v220, v100, v101
	v_cvt_pk_bf16_f32 v221, v102, v103
	v_add_f32_e32 v197, v197, v214
	v_add_f32_e32 v197, v197, v215
	s_waitcnt lgkmcnt(7)
	v_mfma_f32_32x32x16_bf16 v[64:79], v[152:155], v[218:221], v[64:79]
	v_exp_f32_e32 v104, v104
	v_exp_f32_e32 v105, v105
	v_exp_f32_e32 v106, v106
	v_exp_f32_e32 v107, v107
	v_exp_f32_e32 v108, v108
	s_waitcnt lgkmcnt(6)
	v_mfma_f32_32x32x16_bf16 v[48:63], v[10:13], v[218:221], v[48:63]
	v_exp_f32_e32 v109, v109
	v_exp_f32_e32 v110, v110
	v_exp_f32_e32 v111, v111
	v_add_f32_e32 v214, v104, v105
	v_add_f32_e32 v215, v106, v107
	s_waitcnt lgkmcnt(5)
	v_mfma_f32_32x32x16_bf16 v[32:47], v[6:9], v[218:221], v[32:47]
	v_add_f32_e32 v214, v214, v108
	v_add_f32_e32 v215, v215, v109
	v_add_f32_e32 v214, v214, v110
	v_add_f32_e32 v215, v215, v111
	v_cvt_pk_bf16_f32 v222, v104, v105
	s_waitcnt lgkmcnt(4)
	v_mfma_f32_32x32x16_bf16 v[16:31], v[2:5], v[218:221], v[16:31]
	v_cvt_pk_bf16_f32 v223, v106, v107
	v_cvt_pk_bf16_f32 v224, v108, v109
	v_cvt_pk_bf16_f32 v225, v110, v111
	v_add_f32_e32 v197, v197, v214
	v_add_f32_e32 v197, v197, v215
	ds_read_b128 v[152:155], v0 offset:36928
	ds_read_b128 v[10:13], v0 offset:41536
	ds_read_b128 v[6:9], v0 offset:46144
	ds_read_b128 v[2:5], v0 offset:50752
	s_waitcnt lgkmcnt(7)
	v_mfma_f32_32x32x16_bf16 v[64:79], v[198:201], v[222:225], v[64:79]
	v_exp_f32_e32 v80, v80
	v_exp_f32_e32 v81, v81
	v_exp_f32_e32 v82, v82
	v_exp_f32_e32 v83, v83
	v_exp_f32_e32 v84, v84
	s_waitcnt lgkmcnt(6)
	v_mfma_f32_32x32x16_bf16 v[48:63], v[202:205], v[222:225], v[48:63]
	v_exp_f32_e32 v85, v85
	v_exp_f32_e32 v86, v86
	v_exp_f32_e32 v87, v87
	v_add_f32_e32 v214, v80, v81
	v_add_f32_e32 v215, v82, v83
	s_waitcnt lgkmcnt(5)
	v_mfma_f32_32x32x16_bf16 v[32:47], v[206:209], v[222:225], v[32:47]
	v_add_f32_e32 v214, v214, v84
	v_add_f32_e32 v215, v215, v85
	v_add_f32_e32 v214, v214, v86
	v_add_f32_e32 v215, v215, v87
	v_cvt_pk_bf16_f32 v218, v80, v81
	s_waitcnt lgkmcnt(4)
	v_mfma_f32_32x32x16_bf16 v[16:31], v[210:213], v[222:225], v[16:31]
	v_cvt_pk_bf16_f32 v219, v82, v83
	v_cvt_pk_bf16_f32 v220, v84, v85
	v_cvt_pk_bf16_f32 v221, v86, v87
	v_add_f32_e32 v197, v197, v214
	v_add_f32_e32 v197, v197, v215
	ds_read_b128 v[198:201], v0 offset:36960
	ds_read_b128 v[202:205], v0 offset:41568
	ds_read_b128 v[206:209], v0 offset:46176
	ds_read_b128 v[210:213], v0 offset:50784
	s_waitcnt lgkmcnt(7)
	v_mfma_f32_32x32x16_bf16 v[64:79], v[152:155], v[218:221], v[64:79]
	v_exp_f32_e32 v88, v88
	v_exp_f32_e32 v89, v89
	v_exp_f32_e32 v90, v90
	v_exp_f32_e32 v91, v91
	v_exp_f32_e32 v92, v92
	s_waitcnt lgkmcnt(6)
	v_mfma_f32_32x32x16_bf16 v[48:63], v[10:13], v[218:221], v[48:63]
	v_exp_f32_e32 v93, v93
	v_exp_f32_e32 v94, v94
	v_exp_f32_e32 v95, v95
	v_add_f32_e32 v214, v88, v89
	v_add_f32_e32 v215, v90, v91
	s_waitcnt lgkmcnt(5)
	v_mfma_f32_32x32x16_bf16 v[32:47], v[6:9], v[218:221], v[32:47]
	v_add_f32_e32 v214, v214, v92
	v_add_f32_e32 v215, v215, v93
	v_add_f32_e32 v214, v214, v94
	v_add_f32_e32 v215, v215, v95
	v_cvt_pk_bf16_f32 v222, v88, v89
	s_waitcnt lgkmcnt(4)
	v_mfma_f32_32x32x16_bf16 v[16:31], v[2:5], v[218:221], v[16:31]
	v_cvt_pk_bf16_f32 v223, v90, v91
	v_cvt_pk_bf16_f32 v224, v92, v93
	v_cvt_pk_bf16_f32 v225, v94, v95
	v_add_f32_e32 v197, v197, v214
	v_add_f32_e32 v197, v197, v215
	s_waitcnt lgkmcnt(3)
	v_mfma_f32_32x32x16_bf16 v[64:79], v[198:201], v[222:225], v[64:79]
	s_waitcnt lgkmcnt(2)
	v_mfma_f32_32x32x16_bf16 v[48:63], v[202:205], v[222:225], v[48:63]
	s_waitcnt lgkmcnt(1)
	v_mfma_f32_32x32x16_bf16 v[32:47], v[206:209], v[222:225], v[32:47]
	s_waitcnt lgkmcnt(0)
	v_mfma_f32_32x32x16_bf16 v[16:31], v[210:213], v[222:225], v[16:31]
	s_branch .LBB0_124
